# P1 plain (act 0) epilogue path: accumulator moves copy-propagated into the bf16 converts, dead moves and the unused k-max chain removed
# baseline (speedup 1.0000x reference)
.LBB0_185:
	s_and_b64 vcc, exec, s[54:55]
	s_cbranch_vccnz .Lmy_e1_generic
	s_and_b64 vcc, exec, s[74:75]
	s_cbranch_vccnz .Lmy_e1_act1
	s_and_b64 vcc, exec, s[76:77]
	s_cbranch_vccnz .Lmy_e1_act2
	s_and_b64 vcc, exec, s[56:57]
	s_cbranch_vccz .Lmy_e1_act3
	s_xor_b64 s[74:75], s[74:75], -1
	s_xor_b64 s[76:77], s[76:77], -1
	v_mov_b32_e32 v162, 0
	v_mov_b32_e32 v153, v125
	v_mov_b32_e32 v152, v124
	v_mov_b32_e32 v151, v123
	v_mov_b32_e32 v150, v122
	s_mov_b64 s[78:79], 0
	s_lshl_b32 s6, s6, 8
	s_add_i32 s6, s7, s6
	v_or_b32_e32 v122, s6, v156
	s_lshl_b32 s6, s72, 1
	s_add_u32 s6, s38, s6
	v_lshl_add_u32 v161, s8, 8, v154
	s_addc_u32 s7, s39, 0
	v_ashrrev_i32_e32 v123, 31, v122
	v_lshl_add_u64 v[122:123], v[122:123], 1, s[6:7]
	v_mad_i64_i32 v[124:125], s[6:7], s70, v161, 0
	v_lshl_add_u64 v[124:125], v[124:125], 1, v[122:123]
	v_cvt_pk_bf16_f32 v126, v126, v127
	v_cvt_pk_bf16_f32 v127, v128, v129
	v_cvt_pk_bf16_f32 v128, v150, v151
	v_cvt_pk_bf16_f32 v129, v152, v153
	global_store_dwordx4 v[124:125], v[126:129], off
	s_nop 0
	v_mov_b32_e32 v148, v116
	v_mov_b32_e32 v147, v115
	v_mov_b32_e32 v146, v114
	v_cvt_pk_bf16_f32 v114, v118, v119
	v_cvt_pk_bf16_f32 v115, v120, v121
	v_cvt_pk_bf16_f32 v116, v146, v147
	v_cvt_pk_bf16_f32 v117, v148, v117
	global_store_dwordx4 v[124:125], v[114:117], off offset:256
	s_nop 0
	v_mov_b32_e32 v121, v109
	v_mov_b32_e32 v120, v108
	v_mov_b32_e32 v119, v107
	v_mov_b32_e32 v118, v106
	v_or_b32_e32 v106, 16, v161
	v_mad_i64_i32 v[106:107], s[72:73], s70, v106, 0
	v_lshl_add_u64 v[106:107], v[106:107], 1, v[122:123]
	v_cvt_pk_bf16_f32 v108, v110, v111
	v_cvt_pk_bf16_f32 v109, v112, v113
	v_cvt_pk_bf16_f32 v110, v118, v119
	v_cvt_pk_bf16_f32 v111, v120, v121
	global_store_dwordx4 v[106:107], v[108:111], off
	s_nop 0
	v_mov_b32_e32 v114, v100
	v_mov_b32_e32 v113, v99
	v_mov_b32_e32 v112, v98
	v_cvt_pk_bf16_f32 v98, v102, v103
	v_cvt_pk_bf16_f32 v99, v104, v105
	v_cvt_pk_bf16_f32 v100, v112, v113
	v_cvt_pk_bf16_f32 v101, v114, v101
	global_store_dwordx4 v[106:107], v[98:101], off offset:256
	s_nop 0
	v_mov_b32_e32 v105, v93
	v_mov_b32_e32 v104, v92
	v_mov_b32_e32 v103, v91
	v_mov_b32_e32 v102, v90
	v_or_b32_e32 v90, 32, v161
	v_mad_i64_i32 v[90:91], s[72:73], s70, v90, 0
	v_lshl_add_u64 v[90:91], v[90:91], 1, v[122:123]
	v_cvt_pk_bf16_f32 v92, v94, v95
	v_cvt_pk_bf16_f32 v93, v96, v97
	v_cvt_pk_bf16_f32 v94, v102, v103
	v_cvt_pk_bf16_f32 v95, v104, v105
	global_store_dwordx4 v[90:91], v[92:95], off
	s_nop 0
	v_mov_b32_e32 v98, v84
	v_mov_b32_e32 v97, v83
	v_mov_b32_e32 v96, v82
	v_cvt_pk_bf16_f32 v82, v86, v87
	v_cvt_pk_bf16_f32 v83, v88, v89
	v_cvt_pk_bf16_f32 v84, v96, v97
	v_cvt_pk_bf16_f32 v85, v98, v85
	global_store_dwordx4 v[90:91], v[82:85], off offset:256
	s_nop 0
	v_mov_b32_e32 v89, v77
	v_mov_b32_e32 v88, v76
	v_mov_b32_e32 v87, v75
	v_mov_b32_e32 v86, v74
	v_or_b32_e32 v74, 48, v161
	v_mad_i64_i32 v[74:75], s[72:73], s70, v74, 0
	v_lshl_add_u64 v[74:75], v[74:75], 1, v[122:123]
	v_cvt_pk_bf16_f32 v76, v78, v79
	v_cvt_pk_bf16_f32 v77, v80, v81
	v_cvt_pk_bf16_f32 v78, v86, v87
	v_cvt_pk_bf16_f32 v79, v88, v89
	global_store_dwordx4 v[74:75], v[76:79], off
	s_nop 0
	v_mov_b32_e32 v82, v68
	v_mov_b32_e32 v81, v67
	v_mov_b32_e32 v80, v66
	v_cvt_pk_bf16_f32 v66, v70, v71
	v_cvt_pk_bf16_f32 v67, v72, v73
	v_cvt_pk_bf16_f32 v68, v80, v81
	v_cvt_pk_bf16_f32 v69, v82, v69
	global_store_dwordx4 v[74:75], v[66:69], off offset:256
	s_nop 0
	v_mov_b32_e32 v73, v61
	v_mov_b32_e32 v72, v60
	v_mov_b32_e32 v71, v59
	v_mov_b32_e32 v70, v58
	v_add_u32_e32 v58, 0x80, v161
	v_mad_i64_i32 v[58:59], s[72:73], s70, v58, 0
	v_lshl_add_u64 v[58:59], v[58:59], 1, v[122:123]
	v_cvt_pk_bf16_f32 v60, v62, v63
	v_cvt_pk_bf16_f32 v61, v64, v65
	v_cvt_pk_bf16_f32 v62, v70, v71
	v_cvt_pk_bf16_f32 v63, v72, v73
	global_store_dwordx4 v[58:59], v[60:63], off
	s_nop 0
	v_mov_b32_e32 v66, v52
	v_mov_b32_e32 v65, v51
	v_mov_b32_e32 v64, v50
	v_cvt_pk_bf16_f32 v50, v54, v55
	v_cvt_pk_bf16_f32 v51, v56, v57
	v_cvt_pk_bf16_f32 v52, v64, v65
	v_cvt_pk_bf16_f32 v53, v66, v53
	global_store_dwordx4 v[58:59], v[50:53], off offset:256
	s_nop 0
	v_mov_b32_e32 v57, v45
	v_mov_b32_e32 v56, v44
	v_mov_b32_e32 v55, v43
	v_mov_b32_e32 v54, v42
	v_add_u32_e32 v42, 0x90, v161
	v_mad_i64_i32 v[42:43], s[72:73], s70, v42, 0
	v_lshl_add_u64 v[42:43], v[42:43], 1, v[122:123]
	v_cvt_pk_bf16_f32 v44, v46, v47
	v_cvt_pk_bf16_f32 v45, v48, v49
	v_cvt_pk_bf16_f32 v46, v54, v55
	v_cvt_pk_bf16_f32 v47, v56, v57
	global_store_dwordx4 v[42:43], v[44:47], off
	s_nop 0
	v_mov_b32_e32 v50, v36
	v_mov_b32_e32 v49, v35
	v_mov_b32_e32 v48, v34
	v_cvt_pk_bf16_f32 v34, v38, v39
	v_cvt_pk_bf16_f32 v35, v40, v41
	v_cvt_pk_bf16_f32 v36, v48, v49
	v_cvt_pk_bf16_f32 v37, v50, v37
	global_store_dwordx4 v[42:43], v[34:37], off offset:256
	s_nop 0
	v_mov_b32_e32 v41, v29
	v_mov_b32_e32 v40, v28
	v_mov_b32_e32 v39, v27
	v_mov_b32_e32 v38, v26
	v_add_u32_e32 v26, 0xa0, v161
	v_mad_i64_i32 v[26:27], s[72:73], s70, v26, 0
	v_lshl_add_u64 v[26:27], v[26:27], 1, v[122:123]
	v_cvt_pk_bf16_f32 v28, v30, v31
	v_cvt_pk_bf16_f32 v29, v32, v33
	v_cvt_pk_bf16_f32 v30, v38, v39
	v_cvt_pk_bf16_f32 v31, v40, v41
	global_store_dwordx4 v[26:27], v[28:31], off
	s_nop 0
	v_mov_b32_e32 v34, v20
	v_mov_b32_e32 v33, v19
	v_mov_b32_e32 v32, v18
	v_cvt_pk_bf16_f32 v18, v22, v23
	v_cvt_pk_bf16_f32 v19, v24, v25
	v_cvt_pk_bf16_f32 v20, v32, v33
	v_cvt_pk_bf16_f32 v21, v34, v21
	global_store_dwordx4 v[26:27], v[18:21], off offset:256
	s_nop 0
	v_mov_b32_e32 v25, v13
	v_mov_b32_e32 v24, v12
	v_mov_b32_e32 v23, v11
	v_mov_b32_e32 v22, v10
	s_mov_b64 s[72:73], 0
	v_add_u32_e32 v10, 0xb0, v161
	v_mad_i64_i32 v[10:11], s[70:71], s70, v10, 0
	v_lshl_add_u64 v[10:11], v[10:11], 1, v[122:123]
	v_cvt_pk_bf16_f32 v12, v14, v15
	v_cvt_pk_bf16_f32 v13, v16, v17
	v_cvt_pk_bf16_f32 v14, v22, v23
	v_cvt_pk_bf16_f32 v15, v24, v25
	global_store_dwordx4 v[10:11], v[12:15], off
	s_nop 0
	v_mov_b32_e32 v18, v4
	v_mov_b32_e32 v17, v3
	v_mov_b32_e32 v16, v2
	s_mov_b64 s[6:7], 0
	s_mov_b64 s[8:9], 0
	s_and_b64 vcc, exec, s[54:55]
	v_cvt_pk_bf16_f32 v2, v6, v7
	v_cvt_pk_bf16_f32 v3, v8, v9
	v_cvt_pk_bf16_f32 v4, v16, v17
	v_cvt_pk_bf16_f32 v5, v18, v5
	global_store_dwordx4 v[10:11], v[2:5], off offset:256
	s_branch .LBB0_416
